# modnorm and final-norm row sums: DPP reduction plus readlane broadcast instead of six ds_bpermute round trips
# speedup vs baseline: 1.0013x; 1.0013x over previous
.LBB0_31:
	v_add_co_u32_e32 v38, vcc, 0xe9c00000, v32
	global_load_dwordx2 v[36:37], v[32:33], off nt
	s_nop 0
	v_addc_co_u32_e32 v39, vcc, -1, v33, vcc
	v_add_co_u32_e32 v42, vcc, 0xe9c01000, v32
	global_load_dwordx2 v[38:39], v[38:39], off nt
	s_nop 0
	global_load_dwordx2 v[40:41], v[32:33], off offset:512 nt
	v_addc_co_u32_e32 v43, vcc, -1, v33, vcc
	global_load_dwordx2 v[44:45], v[42:43], off offset:-3584 nt
	global_load_dwordx2 v[46:47], v[32:33], off offset:1024 nt
	global_load_dwordx2 v[48:49], v[42:43], off offset:-3072 nt
	global_load_dwordx2 v[50:51], v[32:33], off offset:1536 nt
	global_load_dwordx2 v[52:53], v[42:43], off offset:-2560 nt
	global_load_dwordx2 v[54:55], v[32:33], off offset:2048 nt
	global_load_dwordx2 v[56:57], v[42:43], off offset:-2048 nt
	global_load_dwordx2 v[58:59], v[32:33], off offset:2560 nt
	global_load_dwordx2 v[60:61], v[42:43], off offset:-1536 nt
	global_load_dwordx2 v[62:63], v[32:33], off offset:3072 nt
	global_load_dwordx2 v[64:65], v[42:43], off offset:-1024 nt
	global_load_dwordx2 v[66:67], v[32:33], off offset:3584 nt
	global_load_dwordx2 v[68:69], v[42:43], off offset:-512 nt
	v_cmp_lt_i32_e32 vcc, v232, v231
	s_add_i32 s4, s4, s18
	v_lshl_add_u64 v[32:33], v[32:33], 0, s[44:45]
	s_cmpk_gt_i32 s4, 0x3fff
	s_waitcnt vmcnt(0)
	s_nop 0
	v_cvt_f32_f16_e32 v42, v36
	v_cvt_f32_f16_sdwa v43, v36 dst_sel:DWORD dst_unused:UNUSED_PAD src0_sel:WORD_1
	v_cvt_f32_f16_e32 v36, v37
	v_cvt_f32_f16_sdwa v37, v37 dst_sel:DWORD dst_unused:UNUSED_PAD src0_sel:WORD_1
	v_lshlrev_b32_e32 v70, 16, v38
	v_and_b32_e32 v71, 0xffff0000, v38
	v_lshlrev_b32_e32 v38, 16, v39
	v_and_b32_e32 v39, 0xffff0000, v39
	v_pk_add_f32 v[36:37], v[36:37], v[38:39]
	v_pk_add_f32 v[38:39], v[42:43], v[70:71]
	v_cvt_f32_f16_e32 v42, v40
	v_cvt_f32_f16_sdwa v43, v40 dst_sel:DWORD dst_unused:UNUSED_PAD src0_sel:WORD_1
	v_cvt_f32_f16_e32 v40, v41
	v_cvt_f32_f16_sdwa v41, v41 dst_sel:DWORD dst_unused:UNUSED_PAD src0_sel:WORD_1
	v_lshlrev_b32_e32 v70, 16, v44
	v_and_b32_e32 v71, 0xffff0000, v44
	v_lshlrev_b32_e32 v44, 16, v45
	v_and_b32_e32 v45, 0xffff0000, v45
	v_pk_add_f32 v[40:41], v[40:41], v[44:45]
	v_cvt_f32_f16_e32 v44, v46
	v_cvt_f32_f16_sdwa v45, v46 dst_sel:DWORD dst_unused:UNUSED_PAD src0_sel:WORD_1
	v_cvt_f32_f16_e32 v46, v47
	v_cvt_f32_f16_sdwa v47, v47 dst_sel:DWORD dst_unused:UNUSED_PAD src0_sel:WORD_1
	v_pk_add_f32 v[42:43], v[42:43], v[70:71]
	v_lshlrev_b32_e32 v70, 16, v48
	v_and_b32_e32 v71, 0xffff0000, v48
	v_lshlrev_b32_e32 v48, 16, v49
	v_and_b32_e32 v49, 0xffff0000, v49
	v_pk_add_f32 v[46:47], v[46:47], v[48:49]
	v_cvt_f32_f16_e32 v48, v51
	v_cvt_f32_f16_sdwa v49, v51 dst_sel:DWORD dst_unused:UNUSED_PAD src0_sel:WORD_1
	v_pk_add_f32 v[44:45], v[44:45], v[70:71]
	v_cvt_f32_f16_e32 v70, v50
	v_cvt_f32_f16_sdwa v71, v50 dst_sel:DWORD dst_unused:UNUSED_PAD src0_sel:WORD_1
	v_lshlrev_b32_e32 v50, 16, v52
	v_and_b32_e32 v51, 0xffff0000, v52
	v_lshlrev_b32_e32 v52, 16, v53
	v_and_b32_e32 v53, 0xffff0000, v53
	v_pk_add_f32 v[48:49], v[48:49], v[52:53]
	v_cvt_f32_f16_e32 v52, v55
	v_cvt_f32_f16_sdwa v53, v55 dst_sel:DWORD dst_unused:UNUSED_PAD src0_sel:WORD_1
	v_pk_add_f32 v[50:51], v[70:71], v[50:51]
	v_cvt_f32_f16_e32 v70, v54
	v_cvt_f32_f16_sdwa v71, v54 dst_sel:DWORD dst_unused:UNUSED_PAD src0_sel:WORD_1
	v_lshlrev_b32_e32 v54, 16, v56
	v_and_b32_e32 v55, 0xffff0000, v56
	v_lshlrev_b32_e32 v56, 16, v57
	v_and_b32_e32 v57, 0xffff0000, v57
	v_pk_add_f32 v[52:53], v[52:53], v[56:57]
	v_cvt_f32_f16_e32 v56, v58
	v_cvt_f32_f16_sdwa v57, v58 dst_sel:DWORD dst_unused:UNUSED_PAD src0_sel:WORD_1
	v_cvt_f32_f16_e32 v58, v59
	v_cvt_f32_f16_sdwa v59, v59 dst_sel:DWORD dst_unused:UNUSED_PAD src0_sel:WORD_1
	v_pk_add_f32 v[54:55], v[70:71], v[54:55]
	v_lshlrev_b32_e32 v70, 16, v60
	v_and_b32_e32 v71, 0xffff0000, v60
	v_lshlrev_b32_e32 v60, 16, v61
	v_and_b32_e32 v61, 0xffff0000, v61
	v_pk_add_f32 v[56:57], v[56:57], v[70:71]
	v_cvt_f32_f16_e32 v70, v62
	v_cvt_f32_f16_sdwa v71, v62 dst_sel:DWORD dst_unused:UNUSED_PAD src0_sel:WORD_1
	v_pk_add_f32 v[58:59], v[58:59], v[60:61]
	v_cvt_f32_f16_e32 v60, v63
	v_cvt_f32_f16_sdwa v61, v63 dst_sel:DWORD dst_unused:UNUSED_PAD src0_sel:WORD_1
	v_lshlrev_b32_e32 v62, 16, v64
	v_and_b32_e32 v63, 0xffff0000, v64
	v_lshlrev_b32_e32 v64, 16, v65
	v_and_b32_e32 v65, 0xffff0000, v65
	v_pk_add_f32 v[62:63], v[70:71], v[62:63]
	v_cvt_f32_f16_e32 v70, v66
	v_cvt_f32_f16_sdwa v71, v66 dst_sel:DWORD dst_unused:UNUSED_PAD src0_sel:WORD_1
	v_pk_add_f32 v[60:61], v[60:61], v[64:65]
	v_cvt_f32_f16_e32 v64, v67
	v_cvt_f32_f16_sdwa v65, v67 dst_sel:DWORD dst_unused:UNUSED_PAD src0_sel:WORD_1
	v_lshlrev_b32_e32 v66, 16, v68
	v_and_b32_e32 v67, 0xffff0000, v68
	v_lshlrev_b32_e32 v68, 16, v69
	v_and_b32_e32 v69, 0xffff0000, v69
	v_pk_add_f32 v[66:67], v[70:71], v[66:67]
	v_mov_b32_e32 v70, v39
	v_mov_b32_e32 v71, v43
	v_pk_add_f32 v[64:65], v[64:65], v[68:69]
	v_mov_b32_e32 v68, v38
	v_mov_b32_e32 v69, v42
	v_pk_mul_f32 v[70:71], v[70:71], v[70:71]
	v_mov_b32_e32 v72, v37
	v_mov_b32_e32 v73, v41
	v_pk_fma_f32 v[68:69], v[68:69], v[68:69], v[70:71]
	v_mov_b32_e32 v70, v36
	v_mov_b32_e32 v71, v40
	v_pk_mul_f32 v[72:73], v[72:73], v[72:73]
	s_nop 0
	v_pk_fma_f32 v[70:71], v[70:71], v[70:71], v[72:73]
	v_pk_mul_f32 v[72:73], v[44:45], v[44:45]
	v_pk_add_f32 v[68:69], v[68:69], v[70:71]
	v_pk_mul_f32 v[70:71], v[46:47], v[46:47]
	v_pk_add_f32 v[68:69], v[68:69], v[68:69] op_sel_hi:[0,1]
	v_pk_mov_b32 v[74:75], v[72:73], v[70:71] op_sel:[1,0]
	v_mov_b32_e32 v73, v71
	v_mul_f32_e32 v68, v50, v50
	v_pk_add_f32 v[70:71], v[74:75], v[72:73]
	v_pk_fma_f32 v[72:73], v[50:51], v[50:51], v[68:69] op_sel_hi:[1,1,0]
	v_mul_f32_e32 v68, v48, v48
	v_pk_add_f32 v[70:71], v[70:71], v[70:71] op_sel_hi:[0,1]
	v_pk_fma_f32 v[74:75], v[48:49], v[48:49], v[68:69] op_sel_hi:[1,1,0]
	v_mul_f32_e32 v72, v54, v54
	v_mul_f32_e32 v74, v55, v55
	v_mul_f32_e32 v70, v52, v52
	v_mul_f32_e32 v68, v53, v53
	v_pk_add_f32 v[72:73], v[72:73], v[74:75]
	v_pk_add_f32 v[68:69], v[70:71], v[68:69]
	v_pk_mul_f32 v[70:71], v[58:59], v[58:59]
	v_pk_add_f32 v[68:69], v[72:73], v[68:69]
	v_pk_mul_f32 v[72:73], v[56:57], v[56:57]
	v_pk_add_f32 v[68:69], v[68:69], v[68:69] op_sel_hi:[0,1]
	v_pk_mov_b32 v[74:75], v[72:73], v[70:71] op_sel:[1,0]
	v_mov_b32_e32 v73, v71
	v_mul_f32_e32 v68, v62, v62
	v_pk_add_f32 v[70:71], v[74:75], v[72:73]
	v_pk_fma_f32 v[72:73], v[62:63], v[62:63], v[68:69] op_sel_hi:[1,1,0]
	v_mul_f32_e32 v68, v60, v60
	v_pk_add_f32 v[70:71], v[70:71], v[70:71] op_sel_hi:[0,1]
	v_pk_fma_f32 v[74:75], v[60:61], v[60:61], v[68:69] op_sel_hi:[1,1,0]
	v_mul_f32_e32 v72, v66, v66
	v_mul_f32_e32 v74, v67, v67
	v_mul_f32_e32 v70, v64, v64
	v_mul_f32_e32 v68, v65, v65
	v_pk_add_f32 v[72:73], v[72:73], v[74:75]
	v_pk_add_f32 v[68:69], v[70:71], v[68:69]
	s_nop 0
	v_pk_add_f32 v[68:69], v[72:73], v[68:69]
	s_nop 0
	v_add_f32_e32 v68, v68, v69
	s_nop 1
	v_add_f32_dpp v68, v68, v68 quad_perm:[1,0,3,2] row_mask:0xf bank_mask:0xf
	s_nop 1
	v_add_f32_dpp v68, v68, v68 quad_perm:[2,3,0,1] row_mask:0xf bank_mask:0xf
	s_nop 1
	v_add_f32_dpp v68, v68, v68 row_half_mirror row_mask:0xf bank_mask:0xf
	s_nop 1
	v_add_f32_dpp v68, v68, v68 row_mirror row_mask:0xf bank_mask:0xf
	s_nop 1
	v_add_f32_dpp v68, v68, v68 row_bcast:15 row_mask:0xa bank_mask:0xf
	s_nop 1
	v_add_f32_dpp v68, v68, v68 row_bcast:31 row_mask:0xc bank_mask:0xf
	s_nop 0
	v_readlane_b32 s32, v68, 63
	s_nop 1
	v_mov_b32_e32 v68, s32
	v_fmamk_f32 v68, v68, 0x3a000000, v225
	v_cmp_gt_f32_e32 vcc, s61, v68
	v_mul_f32_e32 v69, 0x4f800000, v68
	s_nop 0
	v_cndmask_b32_e32 v68, v68, v69, vcc
	v_sqrt_f32_e32 v69, v68
	s_nop 0
	v_add_u32_e32 v70, -1, v69
	v_fma_f32 v71, -v70, v69, v68
	v_cmp_ge_f32_e64 s[0:1], 0, v71
	v_add_u32_e32 v71, 1, v69
	s_nop 0
	v_cndmask_b32_e64 v70, v69, v70, s[0:1]
	v_fma_f32 v69, -v71, v69, v68
	v_cmp_lt_f32_e64 s[0:1], 0, v69
	s_nop 1
	v_cndmask_b32_e64 v69, v70, v71, s[0:1]
	v_mul_f32_e32 v70, 0x37800000, v69
	v_cndmask_b32_e32 v69, v69, v70, vcc
	v_cmp_class_f32_e32 vcc, v68, v226
	s_nop 1
	v_cndmask_b32_e32 v68, v69, v68, vcc
	v_div_scale_f32 v69, s[0:1], v68, v68, 1.0
	v_rcp_f32_e32 v70, v69
	s_nop 0
	v_fma_f32 v71, -v69, v70, 1.0
	v_fmac_f32_e32 v70, v71, v70
	v_div_scale_f32 v71, vcc, 1.0, v68, 1.0
	v_mul_f32_e32 v72, v71, v70
	v_fma_f32 v73, -v69, v72, v71
	v_fmac_f32_e32 v72, v73, v70
	v_fma_f32 v69, -v69, v72, v71
	v_div_fmas_f32 v69, v69, v70, v72
	v_div_fixup_f32 v68, v69, v68, 1.0
	v_pk_mul_f32 v[70:71], v[38:39], v[68:69] op_sel_hi:[1,0]
	v_pk_mul_f32 v[36:37], v[36:37], v[68:69] op_sel_hi:[1,0]
	s_nop 0
	v_pk_mul_f32 v[38:39], v[2:3], v[36:37]
	v_pk_mul_f32 v[36:37], v[0:1], v[70:71]
	global_store_dwordx4 v[34:35], v[36:39], off offset:-4096 nt
	s_nop 1
	v_pk_mul_f32 v[36:37], v[42:43], v[68:69] op_sel_hi:[1,0]
	v_pk_mul_f32 v[38:39], v[40:41], v[68:69] op_sel_hi:[1,0]
	v_pk_mul_f32 v[36:37], v[4:5], v[36:37]
	v_pk_mul_f32 v[38:39], v[6:7], v[38:39]
	global_store_dwordx4 v[34:35], v[36:39], off offset:-3072 nt
	s_nop 1
	v_pk_mul_f32 v[36:37], v[44:45], v[68:69] op_sel_hi:[1,0]
	v_pk_mul_f32 v[38:39], v[46:47], v[68:69] op_sel_hi:[1,0]
	v_pk_mul_f32 v[36:37], v[8:9], v[36:37]
	v_pk_mul_f32 v[38:39], v[10:11], v[38:39]
	global_store_dwordx4 v[34:35], v[36:39], off offset:-2048 nt
	s_nop 1
	v_pk_mul_f32 v[36:37], v[50:51], v[68:69] op_sel_hi:[1,0]
	v_pk_mul_f32 v[38:39], v[48:49], v[68:69] op_sel_hi:[1,0]
	v_pk_mul_f32 v[36:37], v[12:13], v[36:37]
	v_pk_mul_f32 v[38:39], v[14:15], v[38:39]
	global_store_dwordx4 v[34:35], v[36:39], off offset:-1024 nt
	s_nop 1
	v_pk_mul_f32 v[36:37], v[54:55], v[68:69] op_sel_hi:[1,0]
	v_pk_mul_f32 v[38:39], v[52:53], v[68:69] op_sel_hi:[1,0]
	v_pk_mul_f32 v[36:37], v[16:17], v[36:37]
	v_pk_mul_f32 v[38:39], v[18:19], v[38:39]
	global_store_dwordx4 v[34:35], v[36:39], off nt
	s_nop 1
	v_pk_mul_f32 v[36:37], v[56:57], v[68:69] op_sel_hi:[1,0]
	v_pk_mul_f32 v[38:39], v[58:59], v[68:69] op_sel_hi:[1,0]
	v_pk_mul_f32 v[36:37], v[20:21], v[36:37]
	v_pk_mul_f32 v[38:39], v[22:23], v[38:39]
	global_store_dwordx4 v[34:35], v[36:39], off offset:1024 nt
	s_nop 1
	v_pk_mul_f32 v[36:37], v[62:63], v[68:69] op_sel_hi:[1,0]
	v_pk_mul_f32 v[38:39], v[60:61], v[68:69] op_sel_hi:[1,0]
	v_pk_mul_f32 v[36:37], v[24:25], v[36:37]
	v_pk_mul_f32 v[38:39], v[26:27], v[38:39]
	global_store_dwordx4 v[34:35], v[36:39], off offset:2048 nt
	s_nop 1
	v_pk_mul_f32 v[36:37], v[66:67], v[68:69] op_sel_hi:[1,0]
	v_pk_mul_f32 v[38:39], v[64:65], v[68:69] op_sel_hi:[1,0]
	v_pk_mul_f32 v[36:37], v[28:29], v[36:37]
	v_pk_mul_f32 v[38:39], v[30:31], v[38:39]
	global_store_dwordx4 v[34:35], v[36:39], off offset:3072 nt
	v_lshl_add_u64 v[34:35], v[34:35], 0, s[12:13]
	s_cbranch_scc0 .LBB0_31

.LBB0_310:
	s_waitcnt vmcnt(11)
	v_pk_mul_f32 v[8:9], v[66:67], v[66:67]
	v_pk_mul_f32 v[10:11], v[70:71], v[70:71]
	s_waitcnt vmcnt(10)
	v_pk_mul_f32 v[12:13], v[68:69], v[68:69]
	v_pk_mul_f32 v[14:15], v[64:65], v[64:65]
	s_waitcnt vmcnt(7)
	v_mov_b32_e32 v17, v12
	v_mov_b32_e32 v16, v14
	v_mov_b32_e32 v12, v15
	v_mov_b32_e32 v14, v8
	v_mov_b32_e32 v15, v10
	v_mov_b32_e32 v10, v9
	v_pk_add_f32 v[12:13], v[16:17], v[12:13]
	v_pk_add_f32 v[8:9], v[14:15], v[10:11]
	v_mov_b32_e32 v10, v132
	v_pk_add_f32 v[8:9], v[12:13], v[8:9]
	v_mov_b32_e32 v12, v133
	v_mov_b32_e32 v13, v129
	v_mov_b32_e32 v11, v128
	v_pk_mul_f32 v[12:13], v[12:13], v[12:13]
	v_mov_b32_e32 v14, v135
	v_mov_b32_e32 v15, v131
	v_pk_fma_f32 v[10:11], v[10:11], v[10:11], v[12:13]
	v_mov_b32_e32 v12, v134
	v_mov_b32_e32 v13, v130
	v_pk_mul_f32 v[14:15], v[14:15], v[14:15]
	v_pk_mul_f32 v[4:5], v[74:75], v[74:75]
	v_pk_mul_f32 v[6:7], v[72:73], v[72:73]
	v_pk_fma_f32 v[12:13], v[12:13], v[12:13], v[14:15]
	v_pk_add_f32 v[8:9], v[8:9], v[8:9] op_sel_hi:[0,1]
	v_pk_add_f32 v[10:11], v[10:11], v[12:13]
	v_pk_mov_b32 v[12:13], v[6:7], v[4:5] op_sel:[1,0]
	v_mov_b32_e32 v7, v5
	v_pk_add_f32 v[4:5], v[12:13], v[6:7]
	v_pk_mul_f32 v[6:7], v[138:139], v[138:139]
	v_pk_add_f32 v[4:5], v[4:5], v[4:5] op_sel_hi:[0,1]
	v_pk_mul_f32 v[12:13], v[136:137], v[136:137]
	v_mul_f32_e32 v4, v76, v76
	v_pk_mov_b32 v[14:15], v[12:13], v[6:7] op_sel:[1,0]
	v_mov_b32_e32 v13, v7
	v_pk_add_f32 v[6:7], v[14:15], v[12:13]
	v_pk_fma_f32 v[12:13], v[76:77], v[76:77], v[4:5] op_sel_hi:[1,1,0]
	v_mul_f32_e32 v4, v78, v78
	v_pk_fma_f32 v[14:15], v[78:79], v[78:79], v[4:5] op_sel_hi:[1,1,0]
	v_mul_f32_e32 v4, v140, v140
	v_pk_fma_f32 v[16:17], v[140:141], v[140:141], v[4:5] op_sel_hi:[1,1,0]
	v_mul_f32_e32 v4, v142, v142
	v_pk_add_f32 v[10:11], v[10:11], v[10:11] op_sel_hi:[0,1]
	v_pk_add_f32 v[6:7], v[6:7], v[6:7] op_sel_hi:[0,1]
	v_pk_fma_f32 v[18:19], v[142:143], v[142:143], v[4:5] op_sel_hi:[1,1,0]
	v_mul_f32_e32 v4, v50, v50
	v_mul_f32_e32 v8, v51, v51
	v_mul_f32_e32 v16, v144, v144
	v_mul_f32_e32 v18, v145, v145
	v_mul_f32_e32 v6, v146, v146
	v_mul_f32_e32 v10, v147, v147
	v_pk_mul_f32 v[0:1], v[86:87], v[86:87]
	v_pk_mul_f32 v[2:3], v[84:85], v[84:85]
	v_pk_add_f32 v[4:5], v[4:5], v[8:9]
	v_pk_add_f32 v[8:9], v[16:17], v[18:19]
	v_pk_add_f32 v[6:7], v[6:7], v[10:11]
	v_mul_f32_e32 v12, v48, v48
	v_pk_add_f32 v[6:7], v[8:9], v[6:7]
	v_pk_mov_b32 v[8:9], v[2:3], v[0:1] op_sel:[1,0]
	v_mov_b32_e32 v3, v1
	v_pk_add_f32 v[0:1], v[8:9], v[2:3]
	v_pk_mul_f32 v[2:3], v[150:151], v[150:151]
	v_pk_add_f32 v[0:1], v[0:1], v[0:1] op_sel_hi:[0,1]
	v_pk_mul_f32 v[8:9], v[148:149], v[148:149]
	v_mul_f32_e32 v14, v49, v49
	v_pk_mov_b32 v[10:11], v[8:9], v[2:3] op_sel:[1,0]
	v_mov_b32_e32 v9, v3
	v_mul_f32_e32 v0, v88, v88
	v_pk_add_f32 v[12:13], v[12:13], v[14:15]
	v_pk_add_f32 v[2:3], v[10:11], v[8:9]
	v_pk_fma_f32 v[8:9], v[88:89], v[88:89], v[0:1] op_sel_hi:[1,1,0]
	v_mul_f32_e32 v0, v90, v90
	v_pk_add_f32 v[4:5], v[12:13], v[4:5]
	v_pk_fma_f32 v[10:11], v[90:91], v[90:91], v[0:1] op_sel_hi:[1,1,0]
	v_mul_f32_e32 v0, v152, v152
	v_pk_add_f32 v[4:5], v[4:5], v[4:5] op_sel_hi:[0,1]
	v_pk_fma_f32 v[12:13], v[152:153], v[152:153], v[0:1] op_sel_hi:[1,1,0]
	v_mul_f32_e32 v0, v154, v154
	v_pk_fma_f32 v[14:15], v[154:155], v[154:155], v[0:1] op_sel_hi:[1,1,0]
	v_mul_f32_e32 v8, v60, v60
	v_mul_f32_e32 v10, v61, v61
	v_mul_f32_e32 v0, v62, v62
	v_mul_f32_e32 v4, v63, v63
	v_pk_add_f32 v[6:7], v[6:7], v[6:7] op_sel_hi:[0,1]
	v_pk_add_f32 v[2:3], v[2:3], v[2:3] op_sel_hi:[0,1]
	v_pk_add_f32 v[8:9], v[8:9], v[10:11]
	v_pk_add_f32 v[0:1], v[0:1], v[4:5]
	v_mul_f32_e32 v12, v156, v156
	v_pk_add_f32 v[0:1], v[8:9], v[0:1]
	v_mul_f32_e32 v14, v157, v157
	v_mul_f32_e32 v2, v158, v158
	v_mul_f32_e32 v6, v159, v159
	v_add_f32_e32 v4, v0, v1
	v_pk_add_f32 v[0:1], v[12:13], v[14:15]
	v_pk_add_f32 v[2:3], v[2:3], v[6:7]
	s_waitcnt vmcnt(3)
	v_add_u32_e32 v24, s12, v162
	v_pk_add_f32 v[0:1], v[0:1], v[2:3]
	s_cmp_eq_u32 s7, 3
	v_add_f32_e32 v1, v0, v1
	s_nop 1
	v_add_f32_dpp v0, v4, v4 quad_perm:[1,0,3,2] row_mask:0xf bank_mask:0xf
	s_nop 1
	v_add_f32_dpp v0, v0, v0 quad_perm:[2,3,0,1] row_mask:0xf bank_mask:0xf
	s_nop 1
	v_add_f32_dpp v0, v0, v0 row_half_mirror row_mask:0xf bank_mask:0xf
	s_nop 1
	v_add_f32_dpp v0, v0, v0 row_mirror row_mask:0xf bank_mask:0xf
	s_nop 1
	v_add_f32_dpp v0, v0, v0 row_bcast:15 row_mask:0xa bank_mask:0xf
	s_nop 1
	v_add_f32_dpp v0, v0, v0 row_bcast:31 row_mask:0xc bank_mask:0xf
	s_nop 0
	v_readlane_b32 s32, v0, 63
	s_waitcnt lgkmcnt(0)
	s_nop 0
	v_mov_b32_e32 v0, s32
	v_fmamk_f32 v0, v0, 0x3a000000, v225
	v_cmp_gt_f32_e32 vcc, s61, v0
	v_mul_f32_e32 v2, 0x4f800000, v0
	s_nop 0
	v_cndmask_b32_e32 v0, v0, v2, vcc
	v_sqrt_f32_e32 v2, v0
	s_nop 0
	v_add_u32_e32 v3, -1, v2
	v_fma_f32 v4, -v3, v2, v0
	v_cmp_ge_f32_e64 s[4:5], 0, v4
	v_add_u32_e32 v4, 1, v2
	s_nop 0
	v_cndmask_b32_e64 v3, v2, v3, s[4:5]
	v_fma_f32 v2, -v4, v2, v0
	v_cmp_lt_f32_e64 s[4:5], 0, v2
	s_nop 1
	v_cndmask_b32_e64 v2, v3, v4, s[4:5]
	v_mul_f32_e32 v3, 0x37800000, v2
	v_cndmask_b32_e32 v2, v2, v3, vcc
	v_cmp_class_f32_e32 vcc, v0, v226
	s_nop 1
	v_cndmask_b32_e32 v0, v2, v0, vcc
	v_div_scale_f32 v2, s[4:5], v0, v0, 1.0
	v_rcp_f32_e32 v3, v2
	s_nop 0
	v_fma_f32 v4, -v2, v3, 1.0
	v_fmac_f32_e32 v3, v4, v3
	v_div_scale_f32 v4, vcc, 1.0, v0, 1.0
	v_mul_f32_e32 v5, v4, v3
	v_fma_f32 v6, -v2, v5, v4
	v_fmac_f32_e32 v5, v6, v3
	v_fma_f32 v2, -v2, v5, v4
	v_div_fmas_f32 v2, v2, v3, v5
	v_div_fixup_f32 v0, v2, v0, 1.0
	s_nop 1
	v_add_f32_dpp v1, v1, v1 quad_perm:[1,0,3,2] row_mask:0xf bank_mask:0xf
	s_nop 1
	v_add_f32_dpp v1, v1, v1 quad_perm:[2,3,0,1] row_mask:0xf bank_mask:0xf
	s_nop 1
	v_add_f32_dpp v1, v1, v1 row_half_mirror row_mask:0xf bank_mask:0xf
	s_nop 1
	v_add_f32_dpp v1, v1, v1 row_mirror row_mask:0xf bank_mask:0xf
	s_nop 1
	v_add_f32_dpp v1, v1, v1 row_bcast:15 row_mask:0xa bank_mask:0xf
	s_nop 1
	v_add_f32_dpp v1, v1, v1 row_bcast:31 row_mask:0xc bank_mask:0xf
	s_nop 0
	v_readlane_b32 s32, v1, 63
	s_waitcnt lgkmcnt(0)
	s_nop 0
	v_mov_b32_e32 v1, s32
	v_fmamk_f32 v1, v1, 0x3a000000, v225
	v_cmp_gt_f32_e32 vcc, s61, v1
	v_mul_f32_e32 v2, 0x4f800000, v1
	s_nop 0
	v_cndmask_b32_e32 v1, v1, v2, vcc
	v_sqrt_f32_e32 v2, v1
	s_nop 0
	v_add_u32_e32 v3, -1, v2
	v_fma_f32 v4, -v3, v2, v1
	v_cmp_ge_f32_e64 s[4:5], 0, v4
	v_add_u32_e32 v4, 1, v2
	s_nop 0
	v_cndmask_b32_e64 v3, v2, v3, s[4:5]
	v_fma_f32 v2, -v4, v2, v1
	v_cmp_lt_f32_e64 s[4:5], 0, v2
	s_nop 1
	v_cndmask_b32_e64 v2, v3, v4, s[4:5]
	v_mul_f32_e32 v3, 0x37800000, v2
	v_cndmask_b32_e32 v2, v2, v3, vcc
	v_cmp_class_f32_e32 vcc, v1, v226
	s_nop 1
	v_cndmask_b32_e32 v1, v2, v1, vcc
	v_div_scale_f32 v2, s[4:5], v1, v1, 1.0
	v_rcp_f32_e32 v3, v2
	v_pk_mul_f32 v[14:15], v[64:65], v[0:1] op_sel_hi:[1,0]
	v_pk_mul_f32 v[16:17], v[66:67], v[0:1] op_sel_hi:[1,0]
	v_fma_f32 v4, -v2, v3, 1.0
	v_fmac_f32_e32 v3, v4, v3
	v_div_scale_f32 v4, vcc, 1.0, v1, 1.0
	v_mul_f32_e32 v5, v4, v3
	v_fma_f32 v6, -v2, v5, v4
	v_fmac_f32_e32 v5, v6, v3
	ds_read_b128 v[6:9], v163
	ds_read_b128 v[10:13], v163 offset:8192
	v_fma_f32 v2, -v2, v5, v4
	v_div_fmas_f32 v2, v2, v3, v5
	v_div_fixup_f32 v4, v2, v1, 1.0
	v_pk_mul_f32 v[18:19], v[128:129], v[4:5] op_sel_hi:[1,0]
	v_lshl_add_u64 v[2:3], v[166:167], 0, s[10:11]
	s_waitcnt lgkmcnt(0)
	v_pk_fma_f32 v[14:15], v[6:7], v[14:15], v[10:11]
	v_pk_mul_f32 v[20:21], v[130:131], v[4:5] op_sel_hi:[1,0]
	v_pk_fma_f32 v[6:7], v[6:7], v[18:19], v[10:11]
	v_pk_fma_f32 v[16:17], v[8:9], v[16:17], v[12:13]
	v_pk_fma_f32 v[8:9], v[8:9], v[20:21], v[12:13]
	v_cvt_pk_bf16_f32 v12, v6, v7
	v_add_co_u32_e32 v6, vcc, s59, v2
	v_cvt_pk_bf16_f32 v10, v14, v15
	v_cvt_pk_bf16_f32 v11, v16, v17
	v_cvt_pk_bf16_f32 v13, v8, v9
	v_addc_co_u32_e32 v7, vcc, 0, v3, vcc
	global_store_dwordx2 v[2:3], v[10:11], off
	global_store_dwordx2 v[6:7], v[12:13], off
	ds_write_b64 v24, v[10:11]
	ds_write_b64 v24, v[12:13] offset:4096
	ds_read_b128 v[8:11], v163 offset:1024
	ds_read_b128 v[12:15], v163 offset:9216
	v_pk_mul_f32 v[16:17], v[68:69], v[0:1] op_sel_hi:[1,0]
	v_pk_mul_f32 v[18:19], v[70:71], v[0:1] op_sel_hi:[1,0]
	v_pk_mul_f32 v[20:21], v[132:133], v[4:5] op_sel_hi:[1,0]
	v_pk_mul_f32 v[22:23], v[134:135], v[4:5] op_sel_hi:[1,0]
	s_waitcnt lgkmcnt(0)
	v_pk_fma_f32 v[18:19], v[10:11], v[18:19], v[14:15]
	v_pk_fma_f32 v[16:17], v[8:9], v[16:17], v[12:13]
	v_pk_fma_f32 v[10:11], v[10:11], v[22:23], v[14:15]
	v_pk_fma_f32 v[8:9], v[8:9], v[20:21], v[12:13]
	v_cvt_pk_bf16_f32 v12, v16, v17
	v_cvt_pk_bf16_f32 v13, v18, v19
	v_cvt_pk_bf16_f32 v8, v8, v9
	v_cvt_pk_bf16_f32 v9, v10, v11
	global_store_dwordx2 v[2:3], v[12:13], off offset:512
	global_store_dwordx2 v[6:7], v[8:9], off offset:512
	ds_write_b64 v24, v[12:13] offset:512
	ds_write_b64 v24, v[8:9] offset:4608
	ds_read_b128 v[8:11], v163 offset:2048
	ds_read_b128 v[12:15], v163 offset:10240
	v_pk_mul_f32 v[16:17], v[72:73], v[0:1] op_sel_hi:[1,0]
	v_pk_mul_f32 v[18:19], v[74:75], v[0:1] op_sel_hi:[1,0]
	v_pk_mul_f32 v[20:21], v[136:137], v[4:5] op_sel_hi:[1,0]
	v_pk_mul_f32 v[22:23], v[138:139], v[4:5] op_sel_hi:[1,0]
	s_waitcnt lgkmcnt(0)
	v_pk_fma_f32 v[18:19], v[18:19], v[10:11], v[14:15]
	v_pk_fma_f32 v[16:17], v[16:17], v[8:9], v[12:13]
	v_pk_fma_f32 v[10:11], v[22:23], v[10:11], v[14:15]
	v_pk_fma_f32 v[8:9], v[20:21], v[8:9], v[12:13]
	v_cvt_pk_bf16_f32 v12, v16, v17
	v_cvt_pk_bf16_f32 v13, v18, v19
	v_cvt_pk_bf16_f32 v8, v8, v9
	v_cvt_pk_bf16_f32 v9, v10, v11
	global_store_dwordx2 v[2:3], v[12:13], off offset:1024
	global_store_dwordx2 v[6:7], v[8:9], off offset:1024
	ds_write_b64 v24, v[12:13] offset:1024
	ds_write_b64 v24, v[8:9] offset:5120
	ds_read_b128 v[8:11], v163 offset:3072
	ds_read_b128 v[12:15], v163 offset:11264
	v_pk_mul_f32 v[16:17], v[76:77], v[0:1] op_sel_hi:[1,0]
	v_pk_mul_f32 v[18:19], v[78:79], v[0:1] op_sel_hi:[1,0]
	v_pk_mul_f32 v[20:21], v[140:141], v[4:5] op_sel_hi:[1,0]
	v_pk_mul_f32 v[22:23], v[142:143], v[4:5] op_sel_hi:[1,0]
	s_waitcnt lgkmcnt(0)
	v_pk_fma_f32 v[18:19], v[18:19], v[10:11], v[14:15]
	v_pk_fma_f32 v[16:17], v[16:17], v[8:9], v[12:13]
	v_pk_fma_f32 v[10:11], v[22:23], v[10:11], v[14:15]
	v_pk_fma_f32 v[8:9], v[20:21], v[8:9], v[12:13]
	v_cvt_pk_bf16_f32 v12, v16, v17
	v_cvt_pk_bf16_f32 v13, v18, v19
	v_cvt_pk_bf16_f32 v8, v8, v9
	v_cvt_pk_bf16_f32 v9, v10, v11
	global_store_dwordx2 v[2:3], v[12:13], off offset:1536
	global_store_dwordx2 v[6:7], v[8:9], off offset:1536
	ds_write_b64 v24, v[12:13] offset:1536
	ds_write_b64 v24, v[8:9] offset:5632
	ds_read_b128 v[8:11], v163 offset:4096
	ds_read_b128 v[12:15], v163 offset:12288
	v_pk_mul_f32 v[16:17], v[80:81], v[0:1] op_sel_hi:[1,0]
	v_pk_mul_f32 v[18:19], v[82:83], v[0:1] op_sel_hi:[1,0]
	v_pk_mul_f32 v[20:21], v[144:145], v[4:5] op_sel_hi:[1,0]
	v_pk_mul_f32 v[22:23], v[146:147], v[4:5] op_sel_hi:[1,0]
	s_waitcnt lgkmcnt(0)
	v_pk_fma_f32 v[18:19], v[18:19], v[10:11], v[14:15]
	v_pk_fma_f32 v[16:17], v[16:17], v[8:9], v[12:13]
	v_pk_fma_f32 v[10:11], v[22:23], v[10:11], v[14:15]
	v_pk_fma_f32 v[8:9], v[20:21], v[8:9], v[12:13]
	v_cvt_pk_bf16_f32 v12, v16, v17
	v_cvt_pk_bf16_f32 v13, v18, v19
	v_cvt_pk_bf16_f32 v8, v8, v9
	v_cvt_pk_bf16_f32 v9, v10, v11
	global_store_dwordx2 v[2:3], v[12:13], off offset:2048
	global_store_dwordx2 v[6:7], v[8:9], off offset:2048
	ds_write_b64 v24, v[12:13] offset:2048
	ds_write_b64 v24, v[8:9] offset:6144
	ds_read_b128 v[8:11], v163 offset:5120
	ds_read_b128 v[12:15], v163 offset:13312
	v_pk_mul_f32 v[16:17], v[84:85], v[0:1] op_sel_hi:[1,0]
	v_pk_mul_f32 v[18:19], v[86:87], v[0:1] op_sel_hi:[1,0]
	v_pk_mul_f32 v[20:21], v[148:149], v[4:5] op_sel_hi:[1,0]
	v_pk_mul_f32 v[22:23], v[150:151], v[4:5] op_sel_hi:[1,0]
	s_waitcnt lgkmcnt(0)
	v_pk_fma_f32 v[18:19], v[18:19], v[10:11], v[14:15]
	v_pk_fma_f32 v[16:17], v[16:17], v[8:9], v[12:13]
	v_pk_fma_f32 v[10:11], v[22:23], v[10:11], v[14:15]
	v_pk_fma_f32 v[8:9], v[20:21], v[8:9], v[12:13]
	v_cvt_pk_bf16_f32 v12, v16, v17
	v_cvt_pk_bf16_f32 v13, v18, v19
	v_cvt_pk_bf16_f32 v8, v8, v9
	v_cvt_pk_bf16_f32 v9, v10, v11
	global_store_dwordx2 v[2:3], v[12:13], off offset:2560
	global_store_dwordx2 v[6:7], v[8:9], off offset:2560
	ds_write_b64 v24, v[12:13] offset:2560
	ds_write_b64 v24, v[8:9] offset:6656
	ds_read_b128 v[8:11], v163 offset:6144
	ds_read_b128 v[12:15], v163 offset:14336
	v_pk_mul_f32 v[16:17], v[88:89], v[0:1] op_sel_hi:[1,0]
	v_pk_mul_f32 v[18:19], v[90:91], v[0:1] op_sel_hi:[1,0]
	v_pk_mul_f32 v[20:21], v[152:153], v[4:5] op_sel_hi:[1,0]
	v_pk_mul_f32 v[22:23], v[154:155], v[4:5] op_sel_hi:[1,0]
	s_waitcnt lgkmcnt(0)
	v_pk_fma_f32 v[18:19], v[18:19], v[10:11], v[14:15]
	v_pk_fma_f32 v[16:17], v[16:17], v[8:9], v[12:13]
	v_pk_fma_f32 v[10:11], v[22:23], v[10:11], v[14:15]
	v_pk_fma_f32 v[8:9], v[20:21], v[8:9], v[12:13]
	v_cvt_pk_bf16_f32 v12, v16, v17
	v_cvt_pk_bf16_f32 v13, v18, v19
	v_cvt_pk_bf16_f32 v8, v8, v9
	v_cvt_pk_bf16_f32 v9, v10, v11
	global_store_dwordx2 v[2:3], v[12:13], off offset:3072
	global_store_dwordx2 v[6:7], v[8:9], off offset:3072
	ds_write_b64 v24, v[12:13] offset:3072
	ds_write_b64 v24, v[8:9] offset:7168
	ds_read_b128 v[8:11], v163 offset:7168
	ds_read_b128 v[12:15], v163 offset:15360
	v_pk_mul_f32 v[16:17], v[92:93], v[0:1] op_sel_hi:[1,0]
	v_pk_mul_f32 v[0:1], v[94:95], v[0:1] op_sel_hi:[1,0]
	v_pk_mul_f32 v[18:19], v[156:157], v[4:5] op_sel_hi:[1,0]
	v_pk_mul_f32 v[4:5], v[158:159], v[4:5] op_sel_hi:[1,0]
	s_waitcnt lgkmcnt(0)
	v_pk_fma_f32 v[0:1], v[0:1], v[10:11], v[14:15]
	v_pk_fma_f32 v[16:17], v[16:17], v[8:9], v[12:13]
	v_pk_fma_f32 v[4:5], v[4:5], v[10:11], v[14:15]
	v_pk_fma_f32 v[8:9], v[18:19], v[8:9], v[12:13]
	v_cvt_pk_bf16_f32 v10, v16, v17
	v_cvt_pk_bf16_f32 v11, v0, v1
	v_cvt_pk_bf16_f32 v0, v8, v9
	v_cvt_pk_bf16_f32 v1, v4, v5
	global_store_dwordx2 v[2:3], v[10:11], off offset:3584
	global_store_dwordx2 v[6:7], v[0:1], off offset:3584
	ds_write_b64 v24, v[10:11] offset:3584
	ds_write_b64 v24, v[0:1] offset:7680
	s_cbranch_scc1 .LBB0_313
	s_add_i32 s4, s8, 2
	s_ashr_i32 s5, s4, 31
	s_lshl_b64 s[10:11], s[4:5], 13
	v_lshl_add_u64 v[16:17], v[160:161], 0, s[10:11]
	v_add_co_u32_e32 v18, vcc, 0x2000, v16
	s_nop 1
	v_addc_co_u32_e32 v19, vcc, 0, v17, vcc
	s_waitcnt vmcnt(18)
	v_add_co_u32_e32 v28, vcc, s59, v16
	global_load_dwordx4 v[0:3], v[16:17], off nt
	global_load_dwordx4 v[4:7], v[16:17], off offset:1024 nt
	global_load_dwordx4 v[96:99], v[18:19], off nt
	global_load_dwordx4 v[100:103], v[18:19], off offset:1024 nt
	global_load_dwordx4 v[8:11], v[16:17], off offset:2048 nt
	global_load_dwordx4 v[12:15], v[16:17], off offset:3072 nt
	global_load_dwordx4 v[104:107], v[18:19], off offset:2048 nt
	global_load_dwordx4 v[108:111], v[18:19], off offset:3072 nt
	v_addc_co_u32_e32 v29, vcc, 0, v17, vcc
	v_add_co_u32_e32 v32, vcc, 0x3000, v16
	s_nop 1
	v_addc_co_u32_e32 v33, vcc, 0, v17, vcc
	global_load_dwordx4 v[16:19], v[28:29], off nt
	global_load_dwordx4 v[20:23], v[28:29], off offset:1024 nt
	global_load_dwordx4 v[112:115], v[32:33], off nt
	global_load_dwordx4 v[116:119], v[32:33], off offset:1024 nt
	global_load_dwordx4 v[24:27], v[28:29], off offset:2048 nt
	s_nop 0
	global_load_dwordx4 v[28:31], v[28:29], off offset:3072 nt
	s_nop 0
	global_load_dwordx4 v[120:123], v[32:33], off offset:2048 nt
	global_load_dwordx4 v[124:127], v[32:33], off offset:3072 nt
	s_andn2_b64 vcc, exec, s[38:39]
	s_cbranch_vccnz .LBB0_314
	s_lshl_b64 s[4:5], s[4:5], 11
	v_lshl_add_u64 v[32:33], s[4:5], 1, v[164:165]
	v_add_co_u32_e32 v34, vcc, 0x1000, v32
	s_nop 1
	v_addc_co_u32_e32 v35, vcc, 0, v33, vcc
	global_load_dwordx2 v[184:185], v[32:33], off
	global_load_dwordx2 v[186:187], v[32:33], off offset:512
	global_load_dwordx2 v[188:189], v[32:33], off offset:1024
	global_load_dwordx2 v[190:191], v[32:33], off offset:1536
	global_load_dwordx2 v[204:205], v[34:35], off
	global_load_dwordx2 v[206:207], v[34:35], off offset:512
	global_load_dwordx2 v[210:211], v[34:35], off offset:1024
	global_load_dwordx2 v[212:213], v[34:35], off offset:1536
	global_load_dwordx2 v[200:201], v[32:33], off offset:2048
	global_load_dwordx2 v[202:203], v[32:33], off offset:2560
	global_load_dwordx2 v[208:209], v[32:33], off offset:3072
	global_load_dwordx2 v[214:215], v[32:33], off offset:3584
	global_load_dwordx2 v[216:217], v[34:35], off offset:2048
	global_load_dwordx2 v[218:219], v[34:35], off offset:2560
	global_load_dwordx2 v[220:221], v[34:35], off offset:3072
	global_load_dwordx2 v[222:223], v[34:35], off offset:3584
	s_branch .LBB0_314
